# ret_m1: per dt-block the 8 transposed LDS reads issued up front into 4 fresh quads with counted lgkmcnt (was 3-4 exposed LDS latencies per block)
# baseline (speedup 1.0000x reference)
.LBB0_1020:
	v_bfe_u32 v88, v98, 2, 4
	v_and_b32_e32 v89, 24, v49
	v_mul_u32_u24_e32 v48, 0x220, v88
	v_mul_u32_u24_e32 v88, 0x120, v88
	s_waitcnt lgkmcnt(0)
	s_barrier
	v_add3_u32 v54, s48, v89, v48
	v_add3_u32 v89, 0, v89, v88
	ds_read_b64_tr_b16 v[74:75], v54 offset:8704
	ds_read_b64_tr_b16 v[72:73], v54
	ds_read_b64_tr_b16 v[76:77], v54 offset:32
	ds_read_b64_tr_b16 v[64:65], v54 offset:17408
	ds_read_b64_tr_b16 v[66:67], v54 offset:26112
	ds_read_b64_tr_b16 v[56:57], v54 offset:34816
	ds_read_b64_tr_b16 v[58:59], v54 offset:43520
	ds_read_b64_tr_b16 v[48:49], v54 offset:52224
	ds_read_b64_tr_b16 v[50:51], v54 offset:60928
	ds_read_b64_tr_b16 v[78:79], v54 offset:8736
	ds_read_b64_tr_b16 v[68:69], v54 offset:17440
	ds_read_b64_tr_b16 v[70:71], v54 offset:26144
	ds_read_b64_tr_b16 v[60:61], v54 offset:34848
	ds_read_b64_tr_b16 v[62:63], v54 offset:43552
	ds_read_b64_tr_b16 v[52:53], v54 offset:52256
	ds_read_b64_tr_b16 v[54:55], v54 offset:60960
	ds_read_b64_tr_b16 v[90:91], v89
	ds_read_b64_tr_b16 v[92:93], v89 offset:4608
	v_and_b32_e32 v86, 15, v98
	v_lshrrev_b32_e32 v80, 1, v98
	ds_read_b64_tr_b16 v[98:99], v89 offset:9216
	ds_read_b64_tr_b16 v[100:101], v89 offset:13824
	s_waitcnt lgkmcnt(2)
	v_mfma_f32_16x16x32_bf16 v[94:97], v[90:93], v[72:75], 0
	v_and_b32_e32 v216, 24, v80
	v_lshl_add_u64 v[82:83], s[6:7], 0, v[216:217]
	v_add_u32_e32 v216, s57, v86
	v_mfma_f32_16x16x32_bf16 v[90:93], v[90:93], v[76:79], 0
	v_lshl_add_u64 v[80:81], s[12:13], 0, v[216:217]
	v_lshlrev_b64 v[80:81], 8, v[80:81]
	v_add_u32_e32 v216, s65, v86
	s_waitcnt lgkmcnt(0)
	v_mfma_f32_16x16x32_bf16 v[94:97], v[98:101], v[64:67], v[94:97]
	v_lshl_add_u64 v[80:81], v[82:83], 0, v[80:81]
	v_lshl_add_u64 v[86:87], s[12:13], 0, v[216:217]
	v_lshlrev_b64 v[86:87], 8, v[86:87]
	v_mfma_f32_16x16x32_bf16 v[90:93], v[98:101], v[68:71], v[90:93]
	ds_read_b64_tr_b16 v[98:99], v89 offset:18432
	ds_read_b64_tr_b16 v[100:101], v89 offset:23040
	v_lshl_add_u64 v[82:83], v[82:83], 0, v[86:87]
	s_mov_b32 s2, 0xffff0000
	s_waitcnt lgkmcnt(0)
	v_mfma_f32_16x16x32_bf16 v[94:97], v[98:101], v[56:59], v[94:97]
	s_mov_b32 s3, -1
	v_lshl_add_u64 v[84:85], v[80:81], 0, s[2:3]
	v_lshl_add_u64 v[86:87], v[82:83], 0, s[2:3]
	v_mfma_f32_16x16x32_bf16 v[90:93], v[98:101], v[60:63], v[90:93]
	ds_read_b64_tr_b16 v[98:99], v89 offset:27648
	ds_read_b64_tr_b16 v[100:101], v89 offset:32256
	v_add_u32_e32 v88, 0x2400, v89
	s_add_u32 s8, s8, s10
	s_waitcnt lgkmcnt(0)
	v_mfma_f32_16x16x32_bf16 v[90:93], v[98:101], v[52:55], v[90:93]
	s_addc_u32 s9, s9, s11
	s_add_u32 s12, s12, s14
	s_addc_u32 s13, s13, s15
	v_mfma_f32_16x16x32_bf16 v[94:97], v[98:101], v[48:51], v[94:97]
	s_nop 3
	v_cvt_pk_bf16_f32 v90, v90, v91
	v_cvt_pk_bf16_f32 v91, v92, v93
	v_add_co_u32_e32 v92, vcc, s72, v80
	s_add_i32 s45, s45, s31
	v_cvt_pk_bf16_f32 v94, v94, v95
	v_cvt_pk_bf16_f32 v95, v96, v97
	v_addc_co_u32_e32 v93, vcc, -1, v81, vcc
	global_store_dwordx2 v[92:93], v[94:95], off
	v_add_co_u32_e32 v92, vcc, s72, v82
	s_mov_b64 s[18:19], -1
	s_nop 0
	v_addc_co_u32_e32 v93, vcc, -1, v83, vcc
	global_store_dwordx2 v[92:93], v[90:91], off
	ds_read_b64_tr_b16 v[144:145], v89 offset:32
	ds_read_b64_tr_b16 v[146:147], v89 offset:4640
	ds_read_b64_tr_b16 v[148:149], v89 offset:9248
	ds_read_b64_tr_b16 v[150:151], v89 offset:13856
	ds_read_b64_tr_b16 v[152:153], v89 offset:18464
	ds_read_b64_tr_b16 v[154:155], v89 offset:23072
	ds_read_b64_tr_b16 v[156:157], v89 offset:27680
	ds_read_b64_tr_b16 v[158:159], v89 offset:32288
	s_waitcnt lgkmcnt(6)
	v_mfma_f32_16x16x32_bf16 v[94:97], v[144:147], v[72:75], 0
	s_andn2_b64 vcc, exec, s[16:17]
	v_mfma_f32_16x16x32_bf16 v[90:93], v[144:147], v[76:79], 0
	s_waitcnt lgkmcnt(4)
	v_mfma_f32_16x16x32_bf16 v[94:97], v[148:151], v[64:67], v[94:97]
	v_mfma_f32_16x16x32_bf16 v[90:93], v[148:151], v[68:71], v[90:93]
	s_waitcnt lgkmcnt(2)
	v_mfma_f32_16x16x32_bf16 v[94:97], v[152:155], v[56:59], v[94:97]
	v_mfma_f32_16x16x32_bf16 v[90:93], v[152:155], v[60:63], v[90:93]
	s_waitcnt lgkmcnt(0)
	v_mfma_f32_16x16x32_bf16 v[94:97], v[156:159], v[48:51], v[94:97]
	v_mfma_f32_16x16x32_bf16 v[90:93], v[156:159], v[52:55], v[90:93]
	s_nop 6
	v_cvt_pk_bf16_f32 v94, v94, v95
	v_cvt_pk_bf16_f32 v95, v96, v97
	v_cvt_pk_bf16_f32 v90, v90, v91
	v_cvt_pk_bf16_f32 v91, v92, v93
	global_store_dwordx2 v[84:85], v[94:95], off offset:32
	global_store_dwordx2 v[86:87], v[90:91], off offset:32
	ds_read_b64_tr_b16 v[144:145], v89 offset:64
	ds_read_b64_tr_b16 v[146:147], v89 offset:4672
	ds_read_b64_tr_b16 v[148:149], v89 offset:9280
	ds_read_b64_tr_b16 v[150:151], v89 offset:13888
	ds_read_b64_tr_b16 v[152:153], v89 offset:18496
	ds_read_b64_tr_b16 v[154:155], v89 offset:23104
	ds_read_b64_tr_b16 v[156:157], v89 offset:27712
	ds_read_b64_tr_b16 v[158:159], v89 offset:32320
	s_waitcnt lgkmcnt(6)
	v_mfma_f32_16x16x32_bf16 v[94:97], v[144:147], v[72:75], 0
	v_mfma_f32_16x16x32_bf16 v[90:93], v[144:147], v[76:79], 0
	s_waitcnt lgkmcnt(4)
	v_mfma_f32_16x16x32_bf16 v[94:97], v[148:151], v[64:67], v[94:97]
	v_mfma_f32_16x16x32_bf16 v[90:93], v[148:151], v[68:71], v[90:93]
	s_waitcnt lgkmcnt(2)
	v_mfma_f32_16x16x32_bf16 v[94:97], v[152:155], v[56:59], v[94:97]
	v_mfma_f32_16x16x32_bf16 v[90:93], v[152:155], v[60:63], v[90:93]
	s_waitcnt lgkmcnt(0)
	v_mfma_f32_16x16x32_bf16 v[94:97], v[156:159], v[48:51], v[94:97]
	v_mfma_f32_16x16x32_bf16 v[90:93], v[156:159], v[52:55], v[90:93]
	s_nop 6
	v_cvt_pk_bf16_f32 v94, v94, v95
	v_cvt_pk_bf16_f32 v95, v96, v97
	v_cvt_pk_bf16_f32 v90, v90, v91
	v_cvt_pk_bf16_f32 v91, v92, v93
	global_store_dwordx2 v[84:85], v[94:95], off offset:64
	global_store_dwordx2 v[86:87], v[90:91], off offset:64
	ds_read_b64_tr_b16 v[144:145], v89 offset:96
	ds_read_b64_tr_b16 v[146:147], v89 offset:4704
	ds_read_b64_tr_b16 v[148:149], v89 offset:9312
	ds_read_b64_tr_b16 v[150:151], v89 offset:13920
	ds_read_b64_tr_b16 v[152:153], v89 offset:18528
	ds_read_b64_tr_b16 v[154:155], v89 offset:23136
	ds_read_b64_tr_b16 v[156:157], v89 offset:27744
	ds_read_b64_tr_b16 v[158:159], v89 offset:32352
	s_waitcnt lgkmcnt(6)
	v_mfma_f32_16x16x32_bf16 v[94:97], v[144:147], v[72:75], 0
	v_mfma_f32_16x16x32_bf16 v[90:93], v[144:147], v[76:79], 0
	s_waitcnt lgkmcnt(4)
	v_mfma_f32_16x16x32_bf16 v[94:97], v[148:151], v[64:67], v[94:97]
	v_mfma_f32_16x16x32_bf16 v[90:93], v[148:151], v[68:71], v[90:93]
	s_waitcnt lgkmcnt(2)
	v_mfma_f32_16x16x32_bf16 v[94:97], v[152:155], v[56:59], v[94:97]
	v_mfma_f32_16x16x32_bf16 v[90:93], v[152:155], v[60:63], v[90:93]
	s_waitcnt lgkmcnt(0)
	v_mfma_f32_16x16x32_bf16 v[94:97], v[156:159], v[48:51], v[94:97]
	v_mfma_f32_16x16x32_bf16 v[90:93], v[156:159], v[52:55], v[90:93]
	s_nop 6
	v_cvt_pk_bf16_f32 v94, v94, v95
	v_cvt_pk_bf16_f32 v95, v96, v97
	v_cvt_pk_bf16_f32 v90, v90, v91
	v_cvt_pk_bf16_f32 v91, v92, v93
	global_store_dwordx2 v[84:85], v[94:95], off offset:96
	global_store_dwordx2 v[86:87], v[90:91], off offset:96
	ds_read_b64_tr_b16 v[144:145], v89 offset:128
	ds_read_b64_tr_b16 v[146:147], v89 offset:4736
	ds_read_b64_tr_b16 v[148:149], v89 offset:9344
	ds_read_b64_tr_b16 v[150:151], v89 offset:13952
	ds_read_b64_tr_b16 v[152:153], v89 offset:18560
	ds_read_b64_tr_b16 v[154:155], v89 offset:23168
	ds_read_b64_tr_b16 v[156:157], v89 offset:27776
	ds_read_b64_tr_b16 v[158:159], v89 offset:32384
	s_waitcnt lgkmcnt(6)
	v_mfma_f32_16x16x32_bf16 v[94:97], v[144:147], v[72:75], 0
	v_mfma_f32_16x16x32_bf16 v[90:93], v[144:147], v[76:79], 0
	s_waitcnt lgkmcnt(4)
	v_mfma_f32_16x16x32_bf16 v[94:97], v[148:151], v[64:67], v[94:97]
	v_mfma_f32_16x16x32_bf16 v[90:93], v[148:151], v[68:71], v[90:93]
	s_waitcnt lgkmcnt(2)
	v_mfma_f32_16x16x32_bf16 v[94:97], v[152:155], v[56:59], v[94:97]
	v_mfma_f32_16x16x32_bf16 v[90:93], v[152:155], v[60:63], v[90:93]
	s_waitcnt lgkmcnt(0)
	v_mfma_f32_16x16x32_bf16 v[94:97], v[156:159], v[48:51], v[94:97]
	v_mfma_f32_16x16x32_bf16 v[90:93], v[156:159], v[52:55], v[90:93]
	s_nop 6
	v_cvt_pk_bf16_f32 v94, v94, v95
	v_cvt_pk_bf16_f32 v95, v96, v97
	v_cvt_pk_bf16_f32 v90, v90, v91
	v_cvt_pk_bf16_f32 v91, v92, v93
	global_store_dwordx2 v[84:85], v[94:95], off offset:128
	global_store_dwordx2 v[86:87], v[90:91], off offset:128
	ds_read_b64_tr_b16 v[144:145], v89 offset:160
	ds_read_b64_tr_b16 v[146:147], v89 offset:4768
	ds_read_b64_tr_b16 v[148:149], v89 offset:9376
	ds_read_b64_tr_b16 v[150:151], v89 offset:13984
	ds_read_b64_tr_b16 v[152:153], v89 offset:18592
	ds_read_b64_tr_b16 v[154:155], v89 offset:23200
	ds_read_b64_tr_b16 v[156:157], v89 offset:27808
	ds_read_b64_tr_b16 v[158:159], v89 offset:32416
	s_waitcnt lgkmcnt(6)
	v_mfma_f32_16x16x32_bf16 v[94:97], v[144:147], v[72:75], 0
	v_mfma_f32_16x16x32_bf16 v[90:93], v[144:147], v[76:79], 0
	s_waitcnt lgkmcnt(4)
	v_mfma_f32_16x16x32_bf16 v[94:97], v[148:151], v[64:67], v[94:97]
	v_mfma_f32_16x16x32_bf16 v[90:93], v[148:151], v[68:71], v[90:93]
	s_waitcnt lgkmcnt(2)
	v_mfma_f32_16x16x32_bf16 v[94:97], v[152:155], v[56:59], v[94:97]
	v_mfma_f32_16x16x32_bf16 v[90:93], v[152:155], v[60:63], v[90:93]
	s_waitcnt lgkmcnt(0)
	v_mfma_f32_16x16x32_bf16 v[94:97], v[156:159], v[48:51], v[94:97]
	v_mfma_f32_16x16x32_bf16 v[90:93], v[156:159], v[52:55], v[90:93]
	s_nop 6
	v_cvt_pk_bf16_f32 v94, v94, v95
	v_cvt_pk_bf16_f32 v95, v96, v97
	v_cvt_pk_bf16_f32 v90, v90, v91
	v_cvt_pk_bf16_f32 v91, v92, v93
	global_store_dwordx2 v[84:85], v[94:95], off offset:160
	global_store_dwordx2 v[86:87], v[90:91], off offset:160
	ds_read_b64_tr_b16 v[144:145], v89 offset:192
	ds_read_b64_tr_b16 v[146:147], v89 offset:4800
	ds_read_b64_tr_b16 v[148:149], v89 offset:9408
	ds_read_b64_tr_b16 v[150:151], v89 offset:14016
	ds_read_b64_tr_b16 v[152:153], v89 offset:18624
	ds_read_b64_tr_b16 v[154:155], v89 offset:23232
	ds_read_b64_tr_b16 v[156:157], v89 offset:27840
	ds_read_b64_tr_b16 v[158:159], v89 offset:32448
	s_waitcnt lgkmcnt(6)
	v_mfma_f32_16x16x32_bf16 v[94:97], v[144:147], v[72:75], 0
	v_mfma_f32_16x16x32_bf16 v[90:93], v[144:147], v[76:79], 0
	s_waitcnt lgkmcnt(4)
	v_mfma_f32_16x16x32_bf16 v[94:97], v[148:151], v[64:67], v[94:97]
	v_mfma_f32_16x16x32_bf16 v[90:93], v[148:151], v[68:71], v[90:93]
	s_waitcnt lgkmcnt(2)
	v_mfma_f32_16x16x32_bf16 v[94:97], v[152:155], v[56:59], v[94:97]
	v_mfma_f32_16x16x32_bf16 v[90:93], v[152:155], v[60:63], v[90:93]
	s_waitcnt lgkmcnt(0)
	v_mfma_f32_16x16x32_bf16 v[94:97], v[156:159], v[48:51], v[94:97]
	v_mfma_f32_16x16x32_bf16 v[90:93], v[156:159], v[52:55], v[90:93]
	s_nop 6
	v_cvt_pk_bf16_f32 v94, v94, v95
	v_cvt_pk_bf16_f32 v95, v96, v97
	v_cvt_pk_bf16_f32 v90, v90, v91
	v_cvt_pk_bf16_f32 v91, v92, v93
	global_store_dwordx2 v[84:85], v[94:95], off offset:192
	global_store_dwordx2 v[86:87], v[90:91], off offset:192
	ds_read_b64_tr_b16 v[90:91], v89 offset:224
	ds_read_b64_tr_b16 v[92:93], v89 offset:4832
	ds_read_b64_tr_b16 v[98:99], v89 offset:9440
	ds_read_b64_tr_b16 v[100:101], v89 offset:14048
	s_waitcnt lgkmcnt(2)
	v_mfma_f32_16x16x32_bf16 v[94:97], v[90:93], v[72:75], 0
	v_mfma_f32_16x16x32_bf16 v[90:93], v[90:93], v[76:79], 0
	s_waitcnt lgkmcnt(0)
	v_mfma_f32_16x16x32_bf16 v[94:97], v[98:101], v[64:67], v[94:97]
	v_mfma_f32_16x16x32_bf16 v[90:93], v[98:101], v[68:71], v[90:93]
	ds_read_b64_tr_b16 v[98:99], v89 offset:18656
	ds_read_b64_tr_b16 v[100:101], v89 offset:23264
	s_waitcnt lgkmcnt(0)
	v_mfma_f32_16x16x32_bf16 v[94:97], v[98:101], v[56:59], v[94:97]
	v_mfma_f32_16x16x32_bf16 v[90:93], v[98:101], v[60:63], v[90:93]
	ds_read_b64_tr_b16 v[98:99], v89 offset:27872
	ds_read_b64_tr_b16 v[100:101], v89 offset:32480
	s_waitcnt lgkmcnt(0)
	v_mfma_f32_16x16x32_bf16 v[94:97], v[98:101], v[48:51], v[94:97]
	v_mfma_f32_16x16x32_bf16 v[90:93], v[98:101], v[52:55], v[90:93]
	s_nop 6
	v_cvt_pk_bf16_f32 v94, v94, v95
	v_cvt_pk_bf16_f32 v95, v96, v97
	v_cvt_pk_bf16_f32 v90, v90, v91
	v_cvt_pk_bf16_f32 v91, v92, v93
	global_store_dwordx2 v[84:85], v[94:95], off offset:224
	global_store_dwordx2 v[86:87], v[90:91], off offset:224
	ds_read_b64_tr_b16 v[144:145], v89 offset:36864
	ds_read_b64_tr_b16 v[146:147], v89 offset:41472
	ds_read_b64_tr_b16 v[148:149], v89 offset:46080
	ds_read_b64_tr_b16 v[150:151], v89 offset:50688
	ds_read_b64_tr_b16 v[152:153], v89 offset:55296
	ds_read_b64_tr_b16 v[154:155], v89 offset:59904
	ds_read_b64_tr_b16 v[156:157], v89 offset:64512
	ds_read_b64_tr_b16 v[158:159], v88 offset:59904
	s_waitcnt lgkmcnt(6)
	v_mfma_f32_16x16x32_bf16 v[90:93], v[144:147], v[72:75], 0
	v_mfma_f32_16x16x32_bf16 v[84:87], v[144:147], v[76:79], 0
	s_waitcnt lgkmcnt(4)
	v_mfma_f32_16x16x32_bf16 v[90:93], v[148:151], v[64:67], v[90:93]
	v_mfma_f32_16x16x32_bf16 v[84:87], v[148:151], v[68:71], v[84:87]
	s_waitcnt lgkmcnt(2)
	v_mfma_f32_16x16x32_bf16 v[90:93], v[152:155], v[56:59], v[90:93]
	v_mfma_f32_16x16x32_bf16 v[84:87], v[152:155], v[60:63], v[84:87]
	s_waitcnt lgkmcnt(0)
	v_mfma_f32_16x16x32_bf16 v[90:93], v[156:159], v[48:51], v[90:93]
	v_mfma_f32_16x16x32_bf16 v[84:87], v[156:159], v[52:55], v[84:87]
	s_nop 6
	v_cvt_pk_bf16_f32 v90, v90, v91
	v_cvt_pk_bf16_f32 v91, v92, v93
	v_cvt_pk_bf16_f32 v84, v84, v85
	v_cvt_pk_bf16_f32 v85, v86, v87
	global_store_dwordx2 v[80:81], v[90:91], off
	global_store_dwordx2 v[82:83], v[84:85], off
	ds_read_b64_tr_b16 v[144:145], v89 offset:36896
	ds_read_b64_tr_b16 v[146:147], v89 offset:41504
	ds_read_b64_tr_b16 v[148:149], v89 offset:46112
	ds_read_b64_tr_b16 v[150:151], v89 offset:50720
	ds_read_b64_tr_b16 v[152:153], v89 offset:55328
	ds_read_b64_tr_b16 v[154:155], v89 offset:59936
	ds_read_b64_tr_b16 v[156:157], v89 offset:64544
	ds_read_b64_tr_b16 v[158:159], v88 offset:59936
	s_waitcnt lgkmcnt(6)
	v_mfma_f32_16x16x32_bf16 v[90:93], v[144:147], v[72:75], 0
	v_mfma_f32_16x16x32_bf16 v[84:87], v[144:147], v[76:79], 0
	s_waitcnt lgkmcnt(4)
	v_mfma_f32_16x16x32_bf16 v[90:93], v[148:151], v[64:67], v[90:93]
	v_mfma_f32_16x16x32_bf16 v[84:87], v[148:151], v[68:71], v[84:87]
	s_waitcnt lgkmcnt(2)
	v_mfma_f32_16x16x32_bf16 v[90:93], v[152:155], v[56:59], v[90:93]
	v_mfma_f32_16x16x32_bf16 v[84:87], v[152:155], v[60:63], v[84:87]
	s_waitcnt lgkmcnt(0)
	v_mfma_f32_16x16x32_bf16 v[90:93], v[156:159], v[48:51], v[90:93]
	v_mfma_f32_16x16x32_bf16 v[84:87], v[156:159], v[52:55], v[84:87]
	s_nop 6
	v_cvt_pk_bf16_f32 v90, v90, v91
	v_cvt_pk_bf16_f32 v91, v92, v93
	v_cvt_pk_bf16_f32 v84, v84, v85
	v_cvt_pk_bf16_f32 v85, v86, v87
	global_store_dwordx2 v[80:81], v[90:91], off offset:32
	global_store_dwordx2 v[82:83], v[84:85], off offset:32
	ds_read_b64_tr_b16 v[144:145], v89 offset:36928
	ds_read_b64_tr_b16 v[146:147], v89 offset:41536
	ds_read_b64_tr_b16 v[148:149], v89 offset:46144
	ds_read_b64_tr_b16 v[150:151], v89 offset:50752
	ds_read_b64_tr_b16 v[152:153], v89 offset:55360
	ds_read_b64_tr_b16 v[154:155], v89 offset:59968
	ds_read_b64_tr_b16 v[156:157], v89 offset:64576
	ds_read_b64_tr_b16 v[158:159], v88 offset:59968
	s_waitcnt lgkmcnt(6)
	v_mfma_f32_16x16x32_bf16 v[90:93], v[144:147], v[72:75], 0
	v_mfma_f32_16x16x32_bf16 v[84:87], v[144:147], v[76:79], 0
	s_waitcnt lgkmcnt(4)
	v_mfma_f32_16x16x32_bf16 v[90:93], v[148:151], v[64:67], v[90:93]
	v_mfma_f32_16x16x32_bf16 v[84:87], v[148:151], v[68:71], v[84:87]
	s_waitcnt lgkmcnt(2)
	v_mfma_f32_16x16x32_bf16 v[90:93], v[152:155], v[56:59], v[90:93]
	v_mfma_f32_16x16x32_bf16 v[84:87], v[152:155], v[60:63], v[84:87]
	s_waitcnt lgkmcnt(0)
	v_mfma_f32_16x16x32_bf16 v[90:93], v[156:159], v[48:51], v[90:93]
	v_mfma_f32_16x16x32_bf16 v[84:87], v[156:159], v[52:55], v[84:87]
	s_nop 6
	v_cvt_pk_bf16_f32 v90, v90, v91
	v_cvt_pk_bf16_f32 v91, v92, v93
	v_cvt_pk_bf16_f32 v84, v84, v85
	v_cvt_pk_bf16_f32 v85, v86, v87
	global_store_dwordx2 v[80:81], v[90:91], off offset:64
	global_store_dwordx2 v[82:83], v[84:85], off offset:64
	ds_read_b64_tr_b16 v[144:145], v89 offset:36960
	ds_read_b64_tr_b16 v[146:147], v89 offset:41568
	ds_read_b64_tr_b16 v[148:149], v89 offset:46176
	ds_read_b64_tr_b16 v[150:151], v89 offset:50784
	ds_read_b64_tr_b16 v[152:153], v89 offset:55392
	ds_read_b64_tr_b16 v[154:155], v89 offset:60000
	ds_read_b64_tr_b16 v[156:157], v89 offset:64608
	ds_read_b64_tr_b16 v[158:159], v88 offset:60000
	s_waitcnt lgkmcnt(6)
	v_mfma_f32_16x16x32_bf16 v[90:93], v[144:147], v[72:75], 0
	v_mfma_f32_16x16x32_bf16 v[84:87], v[144:147], v[76:79], 0
	s_waitcnt lgkmcnt(4)
	v_mfma_f32_16x16x32_bf16 v[90:93], v[148:151], v[64:67], v[90:93]
	v_mfma_f32_16x16x32_bf16 v[84:87], v[148:151], v[68:71], v[84:87]
	s_waitcnt lgkmcnt(2)
	v_mfma_f32_16x16x32_bf16 v[90:93], v[152:155], v[56:59], v[90:93]
	v_mfma_f32_16x16x32_bf16 v[84:87], v[152:155], v[60:63], v[84:87]
	s_waitcnt lgkmcnt(0)
	v_mfma_f32_16x16x32_bf16 v[90:93], v[156:159], v[48:51], v[90:93]
	v_mfma_f32_16x16x32_bf16 v[84:87], v[156:159], v[52:55], v[84:87]
	s_nop 6
	v_cvt_pk_bf16_f32 v90, v90, v91
	v_cvt_pk_bf16_f32 v91, v92, v93
	v_cvt_pk_bf16_f32 v84, v84, v85
	v_cvt_pk_bf16_f32 v85, v86, v87
	global_store_dwordx2 v[80:81], v[90:91], off offset:96
	global_store_dwordx2 v[82:83], v[84:85], off offset:96
	ds_read_b64_tr_b16 v[144:145], v89 offset:36992
	ds_read_b64_tr_b16 v[146:147], v89 offset:41600
	ds_read_b64_tr_b16 v[148:149], v89 offset:46208
	ds_read_b64_tr_b16 v[150:151], v89 offset:50816
	ds_read_b64_tr_b16 v[152:153], v89 offset:55424
	ds_read_b64_tr_b16 v[154:155], v89 offset:60032
	ds_read_b64_tr_b16 v[156:157], v89 offset:64640
	ds_read_b64_tr_b16 v[158:159], v88 offset:60032
	s_waitcnt lgkmcnt(6)
	v_mfma_f32_16x16x32_bf16 v[90:93], v[144:147], v[72:75], 0
	v_mfma_f32_16x16x32_bf16 v[84:87], v[144:147], v[76:79], 0
	s_waitcnt lgkmcnt(4)
	v_mfma_f32_16x16x32_bf16 v[90:93], v[148:151], v[64:67], v[90:93]
	v_mfma_f32_16x16x32_bf16 v[84:87], v[148:151], v[68:71], v[84:87]
	s_waitcnt lgkmcnt(2)
	v_mfma_f32_16x16x32_bf16 v[90:93], v[152:155], v[56:59], v[90:93]
	v_mfma_f32_16x16x32_bf16 v[84:87], v[152:155], v[60:63], v[84:87]
	s_waitcnt lgkmcnt(0)
	v_mfma_f32_16x16x32_bf16 v[90:93], v[156:159], v[48:51], v[90:93]
	v_mfma_f32_16x16x32_bf16 v[84:87], v[156:159], v[52:55], v[84:87]
	s_nop 6
	v_cvt_pk_bf16_f32 v90, v90, v91
	v_cvt_pk_bf16_f32 v91, v92, v93
	v_cvt_pk_bf16_f32 v84, v84, v85
	v_cvt_pk_bf16_f32 v85, v86, v87
	global_store_dwordx2 v[80:81], v[90:91], off offset:128
	global_store_dwordx2 v[82:83], v[84:85], off offset:128
	ds_read_b64_tr_b16 v[144:145], v89 offset:37024
	ds_read_b64_tr_b16 v[146:147], v89 offset:41632
	ds_read_b64_tr_b16 v[148:149], v89 offset:46240
	ds_read_b64_tr_b16 v[150:151], v89 offset:50848
	ds_read_b64_tr_b16 v[152:153], v89 offset:55456
	ds_read_b64_tr_b16 v[154:155], v89 offset:60064
	ds_read_b64_tr_b16 v[156:157], v89 offset:64672
	ds_read_b64_tr_b16 v[158:159], v88 offset:60064
	s_waitcnt lgkmcnt(6)
	v_mfma_f32_16x16x32_bf16 v[90:93], v[144:147], v[72:75], 0
	v_mfma_f32_16x16x32_bf16 v[84:87], v[144:147], v[76:79], 0
	s_waitcnt lgkmcnt(4)
	v_mfma_f32_16x16x32_bf16 v[90:93], v[148:151], v[64:67], v[90:93]
	v_mfma_f32_16x16x32_bf16 v[84:87], v[148:151], v[68:71], v[84:87]
	s_waitcnt lgkmcnt(2)
	v_mfma_f32_16x16x32_bf16 v[90:93], v[152:155], v[56:59], v[90:93]
	v_mfma_f32_16x16x32_bf16 v[84:87], v[152:155], v[60:63], v[84:87]
	s_waitcnt lgkmcnt(0)
	v_mfma_f32_16x16x32_bf16 v[90:93], v[156:159], v[48:51], v[90:93]
	v_mfma_f32_16x16x32_bf16 v[84:87], v[156:159], v[52:55], v[84:87]
	s_nop 6
	v_cvt_pk_bf16_f32 v90, v90, v91
	v_cvt_pk_bf16_f32 v91, v92, v93
	v_cvt_pk_bf16_f32 v84, v84, v85
	v_cvt_pk_bf16_f32 v85, v86, v87
	global_store_dwordx2 v[80:81], v[90:91], off offset:160
	global_store_dwordx2 v[82:83], v[84:85], off offset:160
	ds_read_b64_tr_b16 v[84:85], v89 offset:37056
	ds_read_b64_tr_b16 v[86:87], v89 offset:41664
	ds_read_b64_tr_b16 v[94:95], v89 offset:46272
	ds_read_b64_tr_b16 v[96:97], v89 offset:50880
	s_waitcnt lgkmcnt(2)
	v_mfma_f32_16x16x32_bf16 v[90:93], v[84:87], v[72:75], 0
	v_mfma_f32_16x16x32_bf16 v[84:87], v[84:87], v[76:79], 0
	s_waitcnt lgkmcnt(0)
	v_mfma_f32_16x16x32_bf16 v[90:93], v[94:97], v[64:67], v[90:93]
	v_mfma_f32_16x16x32_bf16 v[84:87], v[94:97], v[68:71], v[84:87]
	ds_read_b64_tr_b16 v[94:95], v89 offset:55488
	ds_read_b64_tr_b16 v[96:97], v89 offset:60096
	s_waitcnt lgkmcnt(0)
	v_mfma_f32_16x16x32_bf16 v[90:93], v[94:97], v[56:59], v[90:93]
	v_mfma_f32_16x16x32_bf16 v[84:87], v[94:97], v[60:63], v[84:87]
	ds_read_b64_tr_b16 v[94:95], v89 offset:64704
	ds_read_b64_tr_b16 v[96:97], v88 offset:60096
	s_waitcnt lgkmcnt(0)
	v_mfma_f32_16x16x32_bf16 v[90:93], v[94:97], v[48:51], v[90:93]
	v_mfma_f32_16x16x32_bf16 v[84:87], v[94:97], v[52:55], v[84:87]
	s_nop 6
	v_cvt_pk_bf16_f32 v90, v90, v91
	v_cvt_pk_bf16_f32 v91, v92, v93
	s_waitcnt vmcnt(36)
	v_mov_b64_e32 v[94:95], v[14:15]
	v_mov_b64_e32 v[92:93], v[12:13]
	v_cvt_pk_bf16_f32 v84, v84, v85
	v_cvt_pk_bf16_f32 v85, v86, v87
	global_store_dwordx2 v[80:81], v[90:91], off offset:192
	global_store_dwordx2 v[82:83], v[84:85], off offset:192
	ds_read_b64_tr_b16 v[84:85], v89 offset:37088
	ds_read_b64_tr_b16 v[86:87], v89 offset:41696
	s_waitcnt lgkmcnt(0)
	v_mfma_f32_16x16x32_bf16 v[72:75], v[84:87], v[72:75], 0
	v_mfma_f32_16x16x32_bf16 v[76:79], v[84:87], v[76:79], 0
	ds_read_b64_tr_b16 v[84:85], v89 offset:46304
	ds_read_b64_tr_b16 v[86:87], v89 offset:50912
	s_waitcnt lgkmcnt(0)
	v_mfma_f32_16x16x32_bf16 v[64:67], v[84:87], v[64:67], v[72:75]
	s_nop 2
	ds_read_b64_tr_b16 v[72:73], v89 offset:55520
	ds_read_b64_tr_b16 v[74:75], v89 offset:60128
	v_mfma_f32_16x16x32_bf16 v[68:71], v[84:87], v[68:71], v[76:79]
	v_mov_b64_e32 v[86:87], v[6:7]
	v_mov_b64_e32 v[84:85], v[4:5]
	s_waitcnt lgkmcnt(0)
	v_mfma_f32_16x16x32_bf16 v[56:59], v[72:75], v[56:59], v[64:67]
	s_nop 2
	ds_read_b64_tr_b16 v[64:65], v89 offset:64736
	ds_read_b64_tr_b16 v[66:67], v88 offset:60128
	s_waitcnt vmcnt(30)
	v_mov_b64_e32 v[78:79], v[46:47]
	v_mov_b64_e32 v[90:91], v[10:11]
	v_mfma_f32_16x16x32_bf16 v[60:63], v[72:75], v[60:63], v[68:71]
	v_mov_b64_e32 v[74:75], v[42:43]
	v_mov_b64_e32 v[72:73], v[40:41]
	v_mov_b64_e32 v[76:77], v[44:45]
	s_waitcnt lgkmcnt(0)
	v_mfma_f32_16x16x32_bf16 v[48:51], v[64:67], v[48:51], v[56:59]
	v_mov_b64_e32 v[70:71], v[38:39]
	v_mov_b64_e32 v[68:69], v[36:37]
	v_mov_b64_e32 v[88:89], v[8:9]
	v_mfma_f32_16x16x32_bf16 v[52:55], v[64:67], v[52:55], v[60:63]
	v_mov_b64_e32 v[58:59], v[22:23]
	s_nop 2
	v_cvt_pk_bf16_f32 v48, v48, v49
	v_cvt_pk_bf16_f32 v49, v50, v51
	v_mov_b64_e32 v[62:63], v[18:19]
	v_mov_b64_e32 v[66:67], v[34:35]
	v_cvt_pk_bf16_f32 v50, v52, v53
	v_cvt_pk_bf16_f32 v51, v54, v55
	global_store_dwordx2 v[80:81], v[48:49], off offset:224
	global_store_dwordx2 v[82:83], v[50:51], off offset:224
	v_mov_b64_e32 v[50:51], v[30:31]
	v_mov_b64_e32 v[54:55], v[26:27]
	v_mov_b64_e32 v[82:83], v[2:3]
	v_mov_b64_e32 v[48:49], v[28:29]
	v_mov_b64_e32 v[52:53], v[24:25]
	v_mov_b64_e32 v[56:57], v[20:21]
	v_mov_b64_e32 v[60:61], v[16:17]
	v_mov_b64_e32 v[64:65], v[32:33]
	v_mov_b64_e32 v[80:81], v[0:1]
	s_cbranch_vccz .LBB0_1036
